# K=2816 sample-row task operands touched into L2 (one dword per 128-B line into unused lanes of the spill VGPR) during the last K-loop iterations of the block's GEMM tiles
# baseline (speedup 1.0000x reference)
.LBB0_636:
	s_cmp_lt_u32 s46, 28
	s_cbranch_scc1 .Lspf_skip
	v_readlane_b32 s98, v252, 29
	s_cmp_eq_u32 s98, 0
	s_cbranch_scc1 .Lspf_skip
	s_sub_u32 s98, s46, 28
	s_lshr_b32 s98, s98, 1
	s_cmp_gt_u32 s98, 5
	s_cbranch_scc1 .Lspf_skip
	v_readlane_b32 s100, v253, 48
	v_readlane_b32 s101, v253, 49
	s_cmp_lt_u32 s98, 2
	s_cbranch_scc0 .Lspf_a
	v_readlane_b32 s99, v253, 41
	s_cmp_lt_u32 s99, 11
	s_cbranch_scc1 .Lspf_l0
	s_add_u32 s100, s100, 0x2800000
	s_addc_u32 s101, s101, 0
	s_sub_u32 s99, s99, 10
.Lspf_l0:
	s_cmp_eq_u32 s99, 2
	s_mov_b32 s99, 0x2280000
	s_cselect_b32 s99, 0xb00000, s99
	s_add_u32 s100, s100, s99
	s_addc_u32 s101, s101, 0
	v_readlane_b32 s99, v251, 0
	s_mul_i32 s99, s99, 0x16000
	s_add_u32 s100, s100, s99
	s_addc_u32 s101, s101, 0
	s_mul_i32 s99, s98, 0xb800
	s_branch .Lspf_go
.Lspf_a:
	s_add_u32 s100, s100, 0x14080000
	s_addc_u32 s101, s101, 0
	s_sub_u32 s99, s98, 2
	s_mul_i32 s99, s99, 0xb800
.Lspf_go:
	s_add_u32 s100, s100, s99
	s_addc_u32 s101, s101, 0
	v_lshrrev_b32_e32 v218, 6, v201
	v_mul_u32_u24_e32 v218, 46, v218
	v_and_b32_e32 v219, 63, v201
	v_add_u32_e32 v218, v218, v219
	v_subrev_u32_e32 v218, 18, v218
	v_lshlrev_b32_e32 v218, 7, v218
	v_mov_b32_e32 v219, 0
	v_lshl_add_u64 v[218:219], s[100:101], 0, v[218:219]
	s_mov_b32 s100, 0xfffc0000
	s_mov_b32 s101, -1
	s_mov_b64 exec, s[100:101]
	s_nop 0
	global_load_dword v255, v[218:219], off
	s_mov_b64 exec, -1

.Lbgc_done2:
	s_mov_b64 s[100:101], 0
	s_branch .LBB0_685
	s_nop 0
	s_nop 0
	s_nop 0
	s_nop 0
	s_nop 0
	s_nop 0
	s_nop 0
	s_nop 0
	s_nop 0
	s_nop 0
	s_nop 0
	s_nop 0
	s_nop 0
	s_nop 0
	s_nop 0
	s_nop 0
	s_nop 0
	s_nop 0
	s_nop 0
	s_nop 0
	s_nop 0
	s_nop 0
	s_nop 0
	s_nop 0
	s_nop 0
	s_nop 0
	s_nop 0
	s_nop 0
	s_nop 0
